# attention: first key block also runs in the pipelined body (forced first rescale), old loop body unreachable
# speedup vs baseline: 1.0073x; 1.0010x over previous
.LBB0_205:
	s_branch .Lfa_entry
	s_waitcnt vmcnt(0) lgkmcnt(0)
	s_barrier
	s_and_b32 s10, s6, 0x8000
	s_cmp_ge_u32 s26, s23
	s_cbranch_scc1 .LBB0_207
	s_xor_b32 s9, s10, 0x8000
	s_sub_i32 s80, s8, 64
	s_add_i32 s9, s9, 0
	s_lshl_b64 s[16:17], s[80:81], 11
	s_add_i32 s11, s9, s24
	v_lshl_add_u64 v[2:3], v[144:145], 0, s[16:17]
	s_mov_b32 m0, s11
	v_lshl_add_u64 v[4:5], v[146:147], 0, s[6:7]
	s_mov_b64 s[16:17], 0x6d08000
	global_load_lds_dwordx4 v[2:3], off
	v_lshl_add_u64 v[2:3], v[2:3], 0, s[60:61]
	s_add_i32 m0, s11, 0x2000
	v_lshl_add_u64 v[6:7], v[4:5], 0, s[16:17]
	global_load_lds_dwordx4 v[2:3], off
	s_add_i32 m0, s11, 0x10000
	s_mov_b64 s[16:17], 0x6d0a000
	s_mov_b32 s9, s81
	global_load_lds_dwordx4 v[6:7], off
	v_lshl_add_u64 v[2:3], v[4:5], 0, s[16:17]
	s_add_i32 m0, s11, 0x12000
	s_lshl_b64 s[16:17], s[8:9], 11
	global_load_lds_dwordx4 v[2:3], off
	v_lshl_add_u64 v[2:3], v[144:145], 0, s[16:17]
	s_add_i32 m0, s11, 0x4000
	s_mov_b64 s[16:17], 0x6d0c000
	global_load_lds_dwordx4 v[2:3], off
	v_lshl_add_u64 v[2:3], v[2:3], 0, s[60:61]
	s_add_i32 m0, s11, 0x6000
	v_lshl_add_u64 v[6:7], v[4:5], 0, s[16:17]
	global_load_lds_dwordx4 v[2:3], off
	s_add_i32 m0, s11, 0x14000
	s_mov_b64 s[16:17], 0x6d0e000
	global_load_lds_dwordx4 v[6:7], off
	v_lshl_add_u64 v[2:3], v[4:5], 0, s[16:17]
	s_add_i32 m0, s11, 0x16000
	s_nop 0
	global_load_lds_dwordx4 v[2:3], off

.Lfa_entry:
	v_add_u32_e32 v0, s20, v156
	v_add_u32_e32 v2, v0, v148
	v_add_u32_e32 v3, v0, v150
	v_add_u32_e32 v4, v0, v152
	v_add_u32_e32 v5, v0, v154
	v_add_u32_e32 v0, s20, v157
	v_add_u32_e32 v0, 0x10000, v0
	v_add_u32_e32 v6, v0, v149
	v_add_u32_e32 v7, v0, v151
	v_add_u32_e32 v8, v0, v153
	v_add_u32_e32 v9, v0, v155
	v_subrev_u32_e32 v10, s86, v144
	v_subrev_u32_e32 v11, s76, v146
	s_waitcnt vmcnt(0) lgkmcnt(0)
	s_barrier
	ds_read_b128 v[160:163], v2
	ds_read_b128 v[164:167], v2 offset:8192
	ds_read_b128 v[168:171], v3
	ds_read_b128 v[224:227], v3 offset:8192
	ds_read_b128 v[228:231], v4
	ds_read_b128 v[232:235], v4 offset:8192
	ds_read_b128 v[236:239], v5
	ds_read_b128 v[244:247], v5 offset:8192
	ds_read_b128 v[248:251], v2 offset:16384
	ds_read_b128 v[252:255], v2 offset:24576
	ds_read_b128 v[148:151], v3 offset:16384
	ds_read_b128 v[152:155], v3 offset:24576
	s_cmp_lt_i32 s26, s5
	s_cbranch_scc0 .Lfa_top_b0
.Lfa_top_0:
	s_barrier
	s_mov_b32 s80, 0
	s_waitcnt lgkmcnt(10)
	v_mfma_f32_32x32x16_bf16 v[96:111], v[160:163], v[128:131], v[80:95]
	ds_read_b128 v[160:163], v4 offset:16384
	s_sub_i32 s16, s8, 64
	s_mov_b32 s17, 0
	s_lshl_b64 s[16:17], s[16:17], 11
	s_add_u32 s16, s16, s86
	s_addc_u32 s17, s17, s87
	s_add_u32 s18, s76, s6
	s_addc_u32 s19, s77, s7
	s_add_u32 s18, s18, 0x6d08000
	s_addc_u32 s19, s19, 0
	s_add_i32 m0, s24, 0x8000
	s_nop 0
	global_load_lds_dwordx4 v10, s[16:17]
	v_mfma_f32_32x32x16_bf16 v[112:127], v[164:167], v[128:131], v[80:95]
	ds_read_b128 v[164:167], v4 offset:24576
	s_add_i32 m0, s24, 0xa000
	s_add_u32 s16, s16, 0x10000
	s_addc_u32 s17, s17, 0
	global_load_lds_dwordx4 v10, s[16:17]
	s_waitcnt lgkmcnt(10)
	v_mfma_f32_32x32x16_bf16 v[96:111], v[168:171], v[132:135], v[96:111]
	ds_read_b128 v[168:171], v5 offset:16384
	s_add_i32 m0, s24, 0x18000
	s_nop 0
	global_load_lds_dwordx4 v11, s[18:19]
	v_mfma_f32_32x32x16_bf16 v[112:127], v[224:227], v[132:135], v[112:127]
	ds_read_b128 v[224:227], v5 offset:24576
	s_add_i32 m0, s24, 0x1a000
	s_add_u32 s18, s18, 0x2000
	s_addc_u32 s19, s19, 0
	global_load_lds_dwordx4 v11, s[18:19]
	s_waitcnt lgkmcnt(10)
	v_mfma_f32_32x32x16_bf16 v[96:111], v[228:231], v[136:139], v[96:111]
	ds_read_b128 v[228:231], v6
	s_add_i32 m0, s24, 0xc000
	s_add_u32 s16, s16, 0x10000
	s_addc_u32 s17, s17, 0
	global_load_lds_dwordx4 v10, s[16:17]
	v_mfma_f32_32x32x16_bf16 v[112:127], v[232:235], v[136:139], v[112:127]
	ds_read_b128 v[232:235], v6 offset:4096
	s_add_i32 m0, s24, 0xe000
	s_add_u32 s16, s16, 0x10000
	s_addc_u32 s17, s17, 0
	global_load_lds_dwordx4 v10, s[16:17]
	s_waitcnt lgkmcnt(10)
	v_mfma_f32_32x32x16_bf16 v[96:111], v[236:239], v[140:143], v[96:111]
	ds_read_b128 v[236:239], v6 offset:8192
	s_add_i32 m0, s24, 0x1c000
	s_add_u32 s18, s18, 0x2000
	s_addc_u32 s19, s19, 0
	global_load_lds_dwordx4 v11, s[18:19]
	v_mfma_f32_32x32x16_bf16 v[112:127], v[244:247], v[140:143], v[112:127]
	ds_read_b128 v[244:247], v6 offset:12288
	s_add_i32 m0, s24, 0x1e000
	s_add_u32 s18, s18, 0x2000
	s_addc_u32 s19, s19, 0
	global_load_lds_dwordx4 v11, s[18:19]
	s_waitcnt lgkmcnt(10)
	v_mfma_f32_32x32x16_bf16 v[192:207], v[248:251], v[128:131], v[80:95]
	ds_read_b128 v[248:251], v7
	s_mov_b64 s[18:19], 0
	v_max3_f32 v190, v96, v97, v98
	v_max3_f32 v190, v190, v99, v100
	v_max3_f32 v190, v190, v101, v102
	v_max3_f32 v190, v190, v103, v104
	v_mfma_f32_32x32x16_bf16 v[208:223], v[252:255], v[128:131], v[80:95]
	ds_read_b128 v[252:255], v7 offset:4096
	v_max3_f32 v190, v190, v105, v106
	v_max3_f32 v190, v190, v107, v108
	v_max3_f32 v190, v190, v109, v110
	v_max3_f32 v190, v190, v111, v111
	v_max3_f32 v191, v112, v113, v114
	v_max3_f32 v191, v191, v115, v116
	s_waitcnt lgkmcnt(10)
	v_mfma_f32_32x32x16_bf16 v[192:207], v[148:151], v[132:135], v[192:207]
	ds_read_b128 v[148:151], v7 offset:8192
	v_max3_f32 v191, v191, v117, v118
	v_max3_f32 v191, v191, v119, v120
	v_max3_f32 v191, v191, v121, v122
	v_max3_f32 v191, v191, v123, v124
	v_max3_f32 v191, v191, v125, v126
	v_max3_f32 v191, v191, v127, v127
	v_mfma_f32_32x32x16_bf16 v[208:223], v[152:155], v[132:135], v[208:223]
	ds_read_b128 v[152:155], v7 offset:12288
	v_max_f32_e32 v0, v190, v191
	s_nop 0
	v_cmp_lt_f32_e32 vcc, s67, v0
	s_cmp_eq_u32 s26, 0
	s_cselect_b64 vcc, exec, vcc
	s_cbranch_vccnz .Lfa_rareA_0

.Lfa_retO_0:
	s_waitcnt lgkmcnt(10)
	v_mfma_f32_32x32x16_bf16 v[64:79], v[248:251], v[192:195], v[64:79]
	ds_read_b128 v[248:251], v9 offset:16384
	v_exp_f32_e32 v200, v200
	v_exp_f32_e32 v201, v201
	v_exp_f32_e32 v202, v202
	v_exp_f32_e32 v203, v203
	v_exp_f32_e32 v204, v204
	v_mfma_f32_32x32x16_bf16 v[48:63], v[252:255], v[192:195], v[48:63]
	ds_read_b128 v[252:255], v9 offset:20480
	v_exp_f32_e32 v205, v205
	v_exp_f32_e32 v206, v206
	v_exp_f32_e32 v207, v207
	v_add_f32_e32 v159, v159, v200
	v_add_f32_e32 v159, v159, v201
	s_waitcnt lgkmcnt(10)
	v_mfma_f32_32x32x16_bf16 v[32:47], v[148:151], v[192:195], v[32:47]
	ds_read_b128 v[148:151], v9 offset:24576
	v_add_f32_e32 v159, v159, v202
	v_add_f32_e32 v159, v159, v203
	v_cvt_pk_bf16_f32 v200, v200, v201
	v_cvt_pk_bf16_f32 v201, v202, v203
	v_add_f32_e32 v159, v159, v204
	v_mfma_f32_32x32x16_bf16 v[16:31], v[152:155], v[192:195], v[16:31]
	ds_read_b128 v[152:155], v9 offset:28672
	v_add_f32_e32 v159, v159, v205
	v_cvt_pk_bf16_f32 v202, v204, v205
	v_cvt_pk_bf16_f32 v203, v206, v207
	v_add_f32_e32 v159, v159, v206
	v_add_f32_e32 v159, v159, v207
	s_waitcnt vmcnt(0)
	s_barrier
	s_waitcnt lgkmcnt(10)
	v_mfma_f32_32x32x16_bf16 v[64:79], v[160:163], v[200:203], v[64:79]
	ds_read_b128 v[160:163], v2 offset:32768
	v_exp_f32_e32 v208, v208
	v_exp_f32_e32 v209, v209
	v_exp_f32_e32 v210, v210
	v_exp_f32_e32 v211, v211
	v_exp_f32_e32 v212, v212
	v_mfma_f32_32x32x16_bf16 v[48:63], v[164:167], v[200:203], v[48:63]
	ds_read_b128 v[164:167], v2 offset:40960
	v_exp_f32_e32 v213, v213
	v_exp_f32_e32 v214, v214
	v_exp_f32_e32 v215, v215
	v_add_f32_e32 v159, v159, v208
	v_add_f32_e32 v159, v159, v209
	s_waitcnt lgkmcnt(10)
	v_mfma_f32_32x32x16_bf16 v[32:47], v[168:171], v[200:203], v[32:47]
	ds_read_b128 v[168:171], v3 offset:32768
	v_add_f32_e32 v159, v159, v210
	v_add_f32_e32 v159, v159, v211
	v_cvt_pk_bf16_f32 v208, v208, v209
	v_cvt_pk_bf16_f32 v209, v210, v211
	v_add_f32_e32 v159, v159, v212
	v_mfma_f32_32x32x16_bf16 v[16:31], v[224:227], v[200:203], v[16:31]
	ds_read_b128 v[224:227], v3 offset:40960
	v_add_f32_e32 v159, v159, v213
	v_cvt_pk_bf16_f32 v210, v212, v213
	v_cvt_pk_bf16_f32 v211, v214, v215
	v_add_f32_e32 v159, v159, v214
	v_add_f32_e32 v159, v159, v215
	s_waitcnt lgkmcnt(10)
	v_mfma_f32_32x32x16_bf16 v[64:79], v[228:231], v[208:211], v[64:79]
	ds_read_b128 v[228:231], v4 offset:32768
	v_exp_f32_e32 v216, v216
	v_exp_f32_e32 v217, v217
	v_exp_f32_e32 v218, v218
	v_exp_f32_e32 v219, v219
	v_exp_f32_e32 v220, v220
	v_mfma_f32_32x32x16_bf16 v[48:63], v[232:235], v[208:211], v[48:63]
	ds_read_b128 v[232:235], v4 offset:40960
	v_exp_f32_e32 v221, v221
	v_exp_f32_e32 v222, v222
	v_exp_f32_e32 v223, v223
	v_add_f32_e32 v159, v159, v216
	v_add_f32_e32 v159, v159, v217
	s_waitcnt lgkmcnt(10)
	v_mfma_f32_32x32x16_bf16 v[32:47], v[236:239], v[208:211], v[32:47]
	ds_read_b128 v[236:239], v5 offset:32768
	v_add_f32_e32 v159, v159, v218
	v_add_f32_e32 v159, v159, v219
	v_cvt_pk_bf16_f32 v216, v216, v217
	v_cvt_pk_bf16_f32 v217, v218, v219
	v_add_f32_e32 v159, v159, v220
	v_mfma_f32_32x32x16_bf16 v[16:31], v[244:247], v[208:211], v[16:31]
	ds_read_b128 v[244:247], v5 offset:40960
	v_add_f32_e32 v159, v159, v221
	v_cvt_pk_bf16_f32 v218, v220, v221
	v_cvt_pk_bf16_f32 v219, v222, v223
	v_add_f32_e32 v159, v159, v222
	v_add_f32_e32 v159, v159, v223
	s_waitcnt lgkmcnt(10)
	v_mfma_f32_32x32x16_bf16 v[64:79], v[248:251], v[216:219], v[64:79]
	ds_read_b128 v[248:251], v2 offset:49152
	s_add_i32 s26, s26, 1
	s_add_u32 s6, s6, 0x8000
	v_mfma_f32_32x32x16_bf16 v[48:63], v[252:255], v[216:219], v[48:63]
	ds_read_b128 v[252:255], v2 offset:57344
	s_addc_u32 s7, s7, 0
	s_addk_i32 s8, 0x80
	s_waitcnt lgkmcnt(10)
	v_mfma_f32_32x32x16_bf16 v[32:47], v[148:151], v[216:219], v[32:47]
	ds_read_b128 v[148:151], v3 offset:49152
	v_add_u32_e32 v158, 0xffffff80, v158
	v_mfma_f32_32x32x16_bf16 v[16:31], v[152:155], v[216:219], v[16:31]
	ds_read_b128 v[152:155], v3 offset:57344
	s_cmp_lt_i32 s26, s5
	s_cbranch_scc0 .Lfa_exit

.Lfa_retO_1:
	s_waitcnt lgkmcnt(10)
	v_mfma_f32_32x32x16_bf16 v[64:79], v[248:251], v[192:195], v[64:79]
	ds_read_b128 v[248:251], v9 offset:49152
	v_exp_f32_e32 v200, v200
	v_exp_f32_e32 v201, v201
	v_exp_f32_e32 v202, v202
	v_exp_f32_e32 v203, v203
	v_exp_f32_e32 v204, v204
	v_mfma_f32_32x32x16_bf16 v[48:63], v[252:255], v[192:195], v[48:63]
	ds_read_b128 v[252:255], v9 offset:53248
	v_exp_f32_e32 v205, v205
	v_exp_f32_e32 v206, v206
	v_exp_f32_e32 v207, v207
	v_add_f32_e32 v159, v159, v200
	v_add_f32_e32 v159, v159, v201
	s_waitcnt lgkmcnt(10)
	v_mfma_f32_32x32x16_bf16 v[32:47], v[148:151], v[192:195], v[32:47]
	ds_read_b128 v[148:151], v9 offset:57344
	v_add_f32_e32 v159, v159, v202
	v_add_f32_e32 v159, v159, v203
	v_cvt_pk_bf16_f32 v200, v200, v201
	v_cvt_pk_bf16_f32 v201, v202, v203
	v_add_f32_e32 v159, v159, v204
	v_mfma_f32_32x32x16_bf16 v[16:31], v[152:155], v[192:195], v[16:31]
	ds_read_b128 v[152:155], v9 offset:61440
	v_add_f32_e32 v159, v159, v205
	v_cvt_pk_bf16_f32 v202, v204, v205
	v_cvt_pk_bf16_f32 v203, v206, v207
	v_add_f32_e32 v159, v159, v206
	v_add_f32_e32 v159, v159, v207
	s_waitcnt vmcnt(0)
	s_barrier
	s_waitcnt lgkmcnt(10)
	v_mfma_f32_32x32x16_bf16 v[64:79], v[160:163], v[200:203], v[64:79]
	ds_read_b128 v[160:163], v2
	v_exp_f32_e32 v208, v208
	v_exp_f32_e32 v209, v209
	v_exp_f32_e32 v210, v210
	v_exp_f32_e32 v211, v211
	v_exp_f32_e32 v212, v212
	v_mfma_f32_32x32x16_bf16 v[48:63], v[164:167], v[200:203], v[48:63]
	ds_read_b128 v[164:167], v2 offset:8192
	v_exp_f32_e32 v213, v213
	v_exp_f32_e32 v214, v214
	v_exp_f32_e32 v215, v215
	v_add_f32_e32 v159, v159, v208
	v_add_f32_e32 v159, v159, v209
	s_waitcnt lgkmcnt(10)
	v_mfma_f32_32x32x16_bf16 v[32:47], v[168:171], v[200:203], v[32:47]
	ds_read_b128 v[168:171], v3
	v_add_f32_e32 v159, v159, v210
	v_add_f32_e32 v159, v159, v211
	v_cvt_pk_bf16_f32 v208, v208, v209
	v_cvt_pk_bf16_f32 v209, v210, v211
	v_add_f32_e32 v159, v159, v212
	v_mfma_f32_32x32x16_bf16 v[16:31], v[224:227], v[200:203], v[16:31]
	ds_read_b128 v[224:227], v3 offset:8192
	v_add_f32_e32 v159, v159, v213
	v_cvt_pk_bf16_f32 v210, v212, v213
	v_cvt_pk_bf16_f32 v211, v214, v215
	v_add_f32_e32 v159, v159, v214
	v_add_f32_e32 v159, v159, v215
	s_waitcnt lgkmcnt(10)
	v_mfma_f32_32x32x16_bf16 v[64:79], v[228:231], v[208:211], v[64:79]
	ds_read_b128 v[228:231], v4
	v_exp_f32_e32 v216, v216
	v_exp_f32_e32 v217, v217
	v_exp_f32_e32 v218, v218
	v_exp_f32_e32 v219, v219
	v_exp_f32_e32 v220, v220
	v_mfma_f32_32x32x16_bf16 v[48:63], v[232:235], v[208:211], v[48:63]
	ds_read_b128 v[232:235], v4 offset:8192
	v_exp_f32_e32 v221, v221
	v_exp_f32_e32 v222, v222
	v_exp_f32_e32 v223, v223
	v_add_f32_e32 v159, v159, v216
	v_add_f32_e32 v159, v159, v217
	s_waitcnt lgkmcnt(10)
	v_mfma_f32_32x32x16_bf16 v[32:47], v[236:239], v[208:211], v[32:47]
	ds_read_b128 v[236:239], v5
	v_add_f32_e32 v159, v159, v218
	v_add_f32_e32 v159, v159, v219
	v_cvt_pk_bf16_f32 v216, v216, v217
	v_cvt_pk_bf16_f32 v217, v218, v219
	v_add_f32_e32 v159, v159, v220
	v_mfma_f32_32x32x16_bf16 v[16:31], v[244:247], v[208:211], v[16:31]
	ds_read_b128 v[244:247], v5 offset:8192
	v_add_f32_e32 v159, v159, v221
	v_cvt_pk_bf16_f32 v218, v220, v221
	v_cvt_pk_bf16_f32 v219, v222, v223
	v_add_f32_e32 v159, v159, v222
	v_add_f32_e32 v159, v159, v223
	s_waitcnt lgkmcnt(10)
	v_mfma_f32_32x32x16_bf16 v[64:79], v[248:251], v[216:219], v[64:79]
	ds_read_b128 v[248:251], v2 offset:16384
	s_add_i32 s26, s26, 1
	s_add_u32 s6, s6, 0x8000
	v_mfma_f32_32x32x16_bf16 v[48:63], v[252:255], v[216:219], v[48:63]
	ds_read_b128 v[252:255], v2 offset:24576
	s_addc_u32 s7, s7, 0
	s_addk_i32 s8, 0x80
	s_waitcnt lgkmcnt(10)
	v_mfma_f32_32x32x16_bf16 v[32:47], v[148:151], v[216:219], v[32:47]
	ds_read_b128 v[148:151], v3 offset:16384
	v_add_u32_e32 v158, 0xffffff80, v158
	v_mfma_f32_32x32x16_bf16 v[16:31], v[152:155], v[216:219], v[16:31]
	ds_read_b128 v[152:155], v3 offset:24576
	s_cmp_lt_i32 s26, s5
	s_cbranch_scc1 .Lfa_top_0

.Lfa_nd7_b0:
	s_mov_b64 s[18:19], 0
	ds_read_b32 v192, v12 offset:0
	ds_read_b32 v193, v12 offset:4
	ds_read_b32 v194, v12 offset:8
	ds_read_b32 v195, v12 offset:12
	ds_read_b32 v196, v12 offset:16
	ds_read_b32 v197, v12 offset:20
	ds_read_b32 v198, v12 offset:24
	ds_read_b32 v199, v12 offset:28
	ds_read_b32 v200, v12 offset:64
	ds_read_b32 v201, v12 offset:68
	ds_read_b32 v202, v12 offset:72
	ds_read_b32 v203, v12 offset:76
	ds_read_b32 v204, v12 offset:80
	ds_read_b32 v205, v12 offset:84
	ds_read_b32 v206, v12 offset:88
	ds_read_b32 v207, v12 offset:92
	ds_read_b32 v208, v12 offset:128
	ds_read_b32 v209, v12 offset:132
	ds_read_b32 v210, v12 offset:136
	ds_read_b32 v211, v12 offset:140
	ds_read_b32 v212, v12 offset:144
	ds_read_b32 v213, v12 offset:148
	ds_read_b32 v214, v12 offset:152
	ds_read_b32 v215, v12 offset:156
	ds_read_b32 v216, v12 offset:192
	ds_read_b32 v217, v12 offset:196
	ds_read_b32 v218, v12 offset:200
	ds_read_b32 v219, v12 offset:204
	ds_read_b32 v220, v12 offset:208
	ds_read_b32 v221, v12 offset:212
	ds_read_b32 v222, v12 offset:216
	ds_read_b32 v223, v12 offset:220
	s_waitcnt lgkmcnt(0)
	v_add_f32_e32 v96, v96, v192
	v_add_f32_e32 v97, v97, v193
	v_add_f32_e32 v98, v98, v194
	v_add_f32_e32 v99, v99, v195
	v_add_f32_e32 v100, v100, v196
	v_add_f32_e32 v101, v101, v197
	v_add_f32_e32 v102, v102, v198
	v_add_f32_e32 v103, v103, v199
	v_add_f32_e32 v104, v104, v200
	v_add_f32_e32 v105, v105, v201
	v_add_f32_e32 v106, v106, v202
	v_add_f32_e32 v107, v107, v203
	v_add_f32_e32 v108, v108, v204
	v_add_f32_e32 v109, v109, v205
	v_add_f32_e32 v110, v110, v206
	v_add_f32_e32 v111, v111, v207
	v_add_f32_e32 v112, v112, v208
	v_add_f32_e32 v113, v113, v209
	v_add_f32_e32 v114, v114, v210
	v_add_f32_e32 v115, v115, v211
	v_add_f32_e32 v116, v116, v212
	v_add_f32_e32 v117, v117, v213
	v_add_f32_e32 v118, v118, v214
	v_add_f32_e32 v119, v119, v215
	v_add_f32_e32 v120, v120, v216
	v_add_f32_e32 v121, v121, v217
	v_add_f32_e32 v122, v122, v218
	v_add_f32_e32 v123, v123, v219
	v_add_f32_e32 v124, v124, v220
	v_add_f32_e32 v125, v125, v221
	v_add_f32_e32 v126, v126, v222
	v_add_f32_e32 v127, v127, v223
	v_max3_f32 v190, v96, v97, v98
	v_max3_f32 v190, v190, v99, v100
	v_max3_f32 v190, v190, v101, v102
	v_max3_f32 v190, v190, v103, v104
	v_max3_f32 v190, v190, v105, v106
	v_max3_f32 v190, v190, v107, v108
	v_max3_f32 v190, v190, v109, v110
	v_max3_f32 v190, v190, v111, v111
	v_max3_f32 v191, v112, v113, v114
	v_max3_f32 v191, v191, v115, v116
	v_max3_f32 v191, v191, v117, v118
	v_max3_f32 v191, v191, v119, v120
	v_max3_f32 v191, v191, v121, v122
	v_max3_f32 v191, v191, v123, v124
	v_max3_f32 v191, v191, v125, v126
	v_max3_f32 v191, v191, v127, v127
	v_max_f32_e32 v0, v190, v191
	s_nop 0
	v_cmp_lt_f32_e32 vcc, s67, v0
	s_cmp_eq_u32 s26, 0
	s_cselect_b64 vcc, exec, vcc
	s_cbranch_vccnz .Lfa_rareA_b0

.Lfa_rareA_0:
	s_nop 7
	v_mov_b32_e32 v15, v0
	s_nop 1
	v_permlane32_swap_b32_e32 v0, v15
	v_max_f32_e32 v0, v0, v15
	v_max_f32_e32 v0, v0, v0
	s_cmp_eq_u32 s26, 0
	s_cbranch_scc1 .Lfa_rA1_0
	v_max_f32_e32 v0, 0, v0
.Lfa_rA1_0:
	s_nop 0
	v_exp_f32_e64 v15, -v0
	v_sub_f32_e32 v96, v96, v0
	v_sub_f32_e32 v97, v97, v0
	v_sub_f32_e32 v98, v98, v0
	v_sub_f32_e32 v99, v99, v0
	v_sub_f32_e32 v100, v100, v0
	v_sub_f32_e32 v101, v101, v0
	v_sub_f32_e32 v102, v102, v0
	v_sub_f32_e32 v103, v103, v0
	v_sub_f32_e32 v104, v104, v0
	v_sub_f32_e32 v105, v105, v0
	v_sub_f32_e32 v106, v106, v0
	v_sub_f32_e32 v107, v107, v0
	v_sub_f32_e32 v108, v108, v0
	v_sub_f32_e32 v109, v109, v0
	v_sub_f32_e32 v110, v110, v0
	v_sub_f32_e32 v111, v111, v0
	v_sub_f32_e32 v112, v112, v0
	v_sub_f32_e32 v113, v113, v0
	v_sub_f32_e32 v114, v114, v0
	v_sub_f32_e32 v115, v115, v0
	v_sub_f32_e32 v116, v116, v0
	v_sub_f32_e32 v117, v117, v0
	v_sub_f32_e32 v118, v118, v0
	v_sub_f32_e32 v119, v119, v0
	v_sub_f32_e32 v120, v120, v0
	v_sub_f32_e32 v121, v121, v0
	v_sub_f32_e32 v122, v122, v0
	v_sub_f32_e32 v123, v123, v0
	v_sub_f32_e32 v124, v124, v0
	v_sub_f32_e32 v125, v125, v0
	v_sub_f32_e32 v126, v126, v0
	v_sub_f32_e32 v127, v127, v0
	v_sub_f32_e32 v80, v80, v0
	v_sub_f32_e32 v81, v81, v0
	v_sub_f32_e32 v82, v82, v0
	v_sub_f32_e32 v83, v83, v0
	v_sub_f32_e32 v84, v84, v0
	v_sub_f32_e32 v85, v85, v0
	v_sub_f32_e32 v86, v86, v0
	v_sub_f32_e32 v87, v87, v0
	v_sub_f32_e32 v88, v88, v0
	v_sub_f32_e32 v89, v89, v0
	v_sub_f32_e32 v90, v90, v0
	v_sub_f32_e32 v91, v91, v0
	v_sub_f32_e32 v92, v92, v0
	v_sub_f32_e32 v93, v93, v0
	v_sub_f32_e32 v94, v94, v0
	v_sub_f32_e32 v95, v95, v0
	v_mul_f32_e32 v16, v16, v15
	v_mul_f32_e32 v17, v17, v15
	v_mul_f32_e32 v18, v18, v15
	v_mul_f32_e32 v19, v19, v15
	v_mul_f32_e32 v20, v20, v15
	v_mul_f32_e32 v21, v21, v15
	v_mul_f32_e32 v22, v22, v15
	v_mul_f32_e32 v23, v23, v15
	v_mul_f32_e32 v24, v24, v15
	v_mul_f32_e32 v25, v25, v15
	v_mul_f32_e32 v26, v26, v15
	v_mul_f32_e32 v27, v27, v15
	v_mul_f32_e32 v28, v28, v15
	v_mul_f32_e32 v29, v29, v15
	v_mul_f32_e32 v30, v30, v15
	v_mul_f32_e32 v31, v31, v15
	v_mul_f32_e32 v32, v32, v15
	v_mul_f32_e32 v33, v33, v15
	v_mul_f32_e32 v34, v34, v15
	v_mul_f32_e32 v35, v35, v15
	v_mul_f32_e32 v36, v36, v15
	v_mul_f32_e32 v37, v37, v15
	v_mul_f32_e32 v38, v38, v15
	v_mul_f32_e32 v39, v39, v15
	v_mul_f32_e32 v40, v40, v15
	v_mul_f32_e32 v41, v41, v15
	v_mul_f32_e32 v42, v42, v15
	v_mul_f32_e32 v43, v43, v15
	v_mul_f32_e32 v44, v44, v15
	v_mul_f32_e32 v45, v45, v15
	v_mul_f32_e32 v46, v46, v15
	v_mul_f32_e32 v47, v47, v15
	v_mul_f32_e32 v48, v48, v15
	v_mul_f32_e32 v49, v49, v15
	v_mul_f32_e32 v50, v50, v15
	v_mul_f32_e32 v51, v51, v15
	v_mul_f32_e32 v52, v52, v15
	v_mul_f32_e32 v53, v53, v15
	v_mul_f32_e32 v54, v54, v15
	v_mul_f32_e32 v55, v55, v15
	v_mul_f32_e32 v56, v56, v15
	v_mul_f32_e32 v57, v57, v15
	v_mul_f32_e32 v58, v58, v15
	v_mul_f32_e32 v59, v59, v15
	v_mul_f32_e32 v60, v60, v15
	v_mul_f32_e32 v61, v61, v15
	v_mul_f32_e32 v62, v62, v15
	v_mul_f32_e32 v63, v63, v15
	v_mul_f32_e32 v64, v64, v15
	v_mul_f32_e32 v65, v65, v15
	v_mul_f32_e32 v66, v66, v15
	v_mul_f32_e32 v67, v67, v15
	v_mul_f32_e32 v68, v68, v15
	v_mul_f32_e32 v69, v69, v15
	v_mul_f32_e32 v70, v70, v15
	v_mul_f32_e32 v71, v71, v15
	v_mul_f32_e32 v72, v72, v15
	v_mul_f32_e32 v73, v73, v15
	v_mul_f32_e32 v74, v74, v15
	v_mul_f32_e32 v75, v75, v15
	v_mul_f32_e32 v76, v76, v15
	v_mul_f32_e32 v77, v77, v15
	v_mul_f32_e32 v78, v78, v15
	v_mul_f32_e32 v79, v79, v15
	v_mul_f32_e32 v159, v159, v15
	v_mov_b32_e32 v14, v0
	s_mov_b64 s[18:19], -1
	s_branch .Lfa_retA_0

.Lfa_rA1_b0:
	s_nop 0
	v_exp_f32_e64 v15, -v0
	v_sub_f32_e32 v96, v96, v0
	v_sub_f32_e32 v97, v97, v0
	v_sub_f32_e32 v98, v98, v0
	v_sub_f32_e32 v99, v99, v0
	v_sub_f32_e32 v100, v100, v0
	v_sub_f32_e32 v101, v101, v0
	v_sub_f32_e32 v102, v102, v0
	v_sub_f32_e32 v103, v103, v0
	v_sub_f32_e32 v104, v104, v0
	v_sub_f32_e32 v105, v105, v0
	v_sub_f32_e32 v106, v106, v0
	v_sub_f32_e32 v107, v107, v0
	v_sub_f32_e32 v108, v108, v0
	v_sub_f32_e32 v109, v109, v0
	v_sub_f32_e32 v110, v110, v0
	v_sub_f32_e32 v111, v111, v0
	v_sub_f32_e32 v112, v112, v0
	v_sub_f32_e32 v113, v113, v0
	v_sub_f32_e32 v114, v114, v0
	v_sub_f32_e32 v115, v115, v0
	v_sub_f32_e32 v116, v116, v0
	v_sub_f32_e32 v117, v117, v0
	v_sub_f32_e32 v118, v118, v0
	v_sub_f32_e32 v119, v119, v0
	v_sub_f32_e32 v120, v120, v0
	v_sub_f32_e32 v121, v121, v0
	v_sub_f32_e32 v122, v122, v0
	v_sub_f32_e32 v123, v123, v0
	v_sub_f32_e32 v124, v124, v0
	v_sub_f32_e32 v125, v125, v0
	v_sub_f32_e32 v126, v126, v0
	v_sub_f32_e32 v127, v127, v0
	v_sub_f32_e32 v80, v80, v0
	v_sub_f32_e32 v81, v81, v0
	v_sub_f32_e32 v82, v82, v0
	v_sub_f32_e32 v83, v83, v0
	v_sub_f32_e32 v84, v84, v0
	v_sub_f32_e32 v85, v85, v0
	v_sub_f32_e32 v86, v86, v0
	v_sub_f32_e32 v87, v87, v0
	v_sub_f32_e32 v88, v88, v0
	v_sub_f32_e32 v89, v89, v0
	v_sub_f32_e32 v90, v90, v0
	v_sub_f32_e32 v91, v91, v0
	v_sub_f32_e32 v92, v92, v0
	v_sub_f32_e32 v93, v93, v0
	v_sub_f32_e32 v94, v94, v0
	v_sub_f32_e32 v95, v95, v0
	v_mul_f32_e32 v16, v16, v15
	v_mul_f32_e32 v17, v17, v15
	v_mul_f32_e32 v18, v18, v15
	v_mul_f32_e32 v19, v19, v15
	v_mul_f32_e32 v20, v20, v15
	v_mul_f32_e32 v21, v21, v15
	v_mul_f32_e32 v22, v22, v15
	v_mul_f32_e32 v23, v23, v15
	v_mul_f32_e32 v24, v24, v15
	v_mul_f32_e32 v25, v25, v15
	v_mul_f32_e32 v26, v26, v15
	v_mul_f32_e32 v27, v27, v15
	v_mul_f32_e32 v28, v28, v15
	v_mul_f32_e32 v29, v29, v15
	v_mul_f32_e32 v30, v30, v15
	v_mul_f32_e32 v31, v31, v15
	v_mul_f32_e32 v32, v32, v15
	v_mul_f32_e32 v33, v33, v15
	v_mul_f32_e32 v34, v34, v15
	v_mul_f32_e32 v35, v35, v15
	v_mul_f32_e32 v36, v36, v15
	v_mul_f32_e32 v37, v37, v15
	v_mul_f32_e32 v38, v38, v15
	v_mul_f32_e32 v39, v39, v15
	v_mul_f32_e32 v40, v40, v15
	v_mul_f32_e32 v41, v41, v15
	v_mul_f32_e32 v42, v42, v15
	v_mul_f32_e32 v43, v43, v15
	v_mul_f32_e32 v44, v44, v15
	v_mul_f32_e32 v45, v45, v15
	v_mul_f32_e32 v46, v46, v15
	v_mul_f32_e32 v47, v47, v15
	v_mul_f32_e32 v48, v48, v15
	v_mul_f32_e32 v49, v49, v15
	v_mul_f32_e32 v50, v50, v15
	v_mul_f32_e32 v51, v51, v15
	v_mul_f32_e32 v52, v52, v15
	v_mul_f32_e32 v53, v53, v15
	v_mul_f32_e32 v54, v54, v15
	v_mul_f32_e32 v55, v55, v15
	v_mul_f32_e32 v56, v56, v15
	v_mul_f32_e32 v57, v57, v15
	v_mul_f32_e32 v58, v58, v15
	v_mul_f32_e32 v59, v59, v15
	v_mul_f32_e32 v60, v60, v15
	v_mul_f32_e32 v61, v61, v15
	v_mul_f32_e32 v62, v62, v15
	v_mul_f32_e32 v63, v63, v15
	v_mul_f32_e32 v64, v64, v15
	v_mul_f32_e32 v65, v65, v15
	v_mul_f32_e32 v66, v66, v15
	v_mul_f32_e32 v67, v67, v15
	v_mul_f32_e32 v68, v68, v15
	v_mul_f32_e32 v69, v69, v15
	v_mul_f32_e32 v70, v70, v15
	v_mul_f32_e32 v71, v71, v15
	v_mul_f32_e32 v72, v72, v15
	v_mul_f32_e32 v73, v73, v15
	v_mul_f32_e32 v74, v74, v15
	v_mul_f32_e32 v75, v75, v15
	v_mul_f32_e32 v76, v76, v15
	v_mul_f32_e32 v77, v77, v15
	v_mul_f32_e32 v78, v78, v15
	v_mul_f32_e32 v79, v79, v15
	v_mul_f32_e32 v159, v159, v15
	s_nop 1
	s_branch .Lfa_retA_b0
